# scan phase: workgroup->item remap so the 8 workgroups sharing one (b,h) Q/K stream sit on one XCD
# speedup vs baseline: 1.0199x; 1.0076x over previous
.LBB0_359:
	s_cmpk_gt_i32 s2, 0xff
	s_barrier
	s_waitcnt vmcnt(7)
	v_mbcnt_lo_u32_b32 v0, -1, 0
	v_mbcnt_hi_u32_b32 v0, -1, v0
	s_cbranch_scc1 .LBB0_366
	v_readlane_b32 s0, v255, 1
	s_movk_i32 s16, 0x3000
	v_bfe_u32 v3, v0, 5, 1
	v_add_u32_e32 v2, s0, v0
	s_waitcnt vmcnt(6)
	v_ashrrev_i32_e32 v7, 5, v2
	s_waitcnt vmcnt(4)
	v_ashrrev_i32_e32 v10, 3, v2
	v_mad_i64_i32 v[148:149], s[0:1], v7, s16, 0
	v_mad_i64_i32 v[152:153], s[0:1], v10, s16, 0
	s_movk_i32 s0, 0xc0
	v_lshrrev_b32_e32 v1, 2, v0
	v_and_b32_e32 v5, 31, v0
	v_lshlrev_b32_e32 v150, 3, v3
	v_mul_lo_u32 v9, v10, s0
	s_add_i32 s0, 0, 0x11200
	v_or_b32_e32 v4, 32, v5
	v_and_b32_e32 v8, 7, v0
	v_add_u32_e32 v11, s0, v9
	v_readlane_b32 s10, v255, 0
	v_and_or_b32 v1, v1, 3, v150
	v_lshlrev_b32_e32 v9, 1, v0
	v_cvt_f32_ubyte0_e32 v157, v4
	v_lshlrev_b32_e32 v4, 3, v8
	s_waitcnt vmcnt(2)
	v_lshlrev_b32_e32 v12, 4, v8
	s_and_b32 s12, s10, 0xffffff80
	v_mul_u32_u24_e32 v8, 0xc0, v1
	v_and_b32_e32 v9, 32, v9
	v_lshlrev_b32_e32 v15, 3, v0
	v_readlane_b32 s11, v255, 30
	s_add_i32 s4, s12, 0
	v_and_b32_e32 v15, 24, v15
	v_add3_u32 v8, s0, v8, v9
	v_readlane_b32 s0, v255, 31
	v_readlane_b32 s13, v255, 40
	v_add_u32_e32 v14, s4, v150
	v_add3_u32 v219, v8, s0, v15
	v_lshl_or_b32 v8, s11, 6, v5
	s_add_i32 s4, 0, 0x14200
	s_lshl_b32 s0, s13, 7
	s_movk_i32 s7, 0x104
	s_movk_i32 s1, 0x208
	s_add_i32 s0, s0, s4
	v_mul_lo_u32 v8, v8, s7
	v_lshlrev_b32_e32 v3, 4, v3
	v_add3_u32 v220, s0, v3, v8
	s_movk_i32 s0, 0x240
	v_mul_lo_u32 v221, v7, s1
	v_cvt_f32_ubyte0_e32 v155, v5
	v_mad_u32_u24 v1, v1, s0, 0
	v_add_u32_e32 v154, 0, v221
	v_add3_u32 v15, v1, v15, v9
	v_mul_lo_u32 v222, v7, s0
	v_mad_u64_u32 v[8:9], s[0:1], v7, 56, v[154:155]
	s_lshl_b32 s6, s11, 4
	s_lshl_b32 s0, s11, 7
	v_lshlrev_b32_e32 v0, 5, v0
	s_add_u32 s0, s62, s0
	v_mov_b32_e32 v151, 0
	v_mul_lo_u32 v1, v10, s7
	v_and_b32_e32 v0, 0xe0, v0
	s_addc_u32 s1, s63, 0
	v_add3_u32 v223, s4, v1, v0
	v_lshl_add_u64 v[0:1], s[0:1], 0, v[150:151]
	s_mov_b64 s[0:1], 0x18000000
	v_lshl_add_u64 v[158:159], v[0:1], 0, s[0:1]
	v_or_b32_e32 v0, v152, v12
	v_mov_b32_e32 v1, v153
	s_lshr_b32 s0, s10, 2
	s_mov_b32 s5, 0
	v_lshl_add_u64 v[160:161], s[62:63], 0, v[0:1]
	v_lshlrev_b32_e32 v0, 7, v5
	v_mov_b32_e32 v1, v151
	s_and_b32 s4, s0, 0x3fffffe0
	v_lshl_add_u64 v[0:1], v[0:1], 0, s[4:5]
	v_lshlrev_b32_e32 v217, 4, v5
	v_or_b32_e32 v0, v0, v3
	v_lshlrev_b32_e32 v2, 3, v5
	v_lshlrev_b32_e32 v6, 6, v5
	v_add_u32_e32 v218, 0, v217
	v_mul_u32_u24_e32 v13, 0x208, v5
	v_add_u32_e32 v7, 0x2080, v221
	v_add_u32_e32 v9, 0x2400, v222
	v_lshl_add_u64 v[0:1], s[60:61], 0, v[0:1]
	s_mov_b64 s[0:1], 0x3000
	s_mul_i32 s17, s11, 0xc00
	v_add_u32_e32 v224, 8, v223
	v_add_u32_e32 v225, 16, v223
	v_add_u32_e32 v226, 24, v223
	v_lshl_or_b32 v156, s13, 5, v5
	s_and_b32 s100, s2, 7
	s_lshl_b32 s100, s100, 2
	s_lshr_b32 s101, s2, 6
	s_add_i32 s100, s100, s101
	s_lshl_b32 s100, s100, 3
	s_bfe_u32 s101, s2, 0x30003
	s_or_b32 s100, s100, s101
	s_cmp_lg_u32 s33, 0x100
	s_cselect_b32 s100, s2, s100
	s_lshl_b32 s18, s100, 6
	s_lshl_b32 s19, s33, 6
	v_lshl_add_u64 v[162:163], v[0:1], 0, s[0:1]
	s_mov_b32 s20, 0xc2fc0000
	v_lshlrev_b32_e32 v164, 1, v2
	v_lshlrev_b32_e32 v166, 1, v6
	s_lshl_b32 s6, s6, 1
	s_mov_b32 s7, s5
	s_mov_b32 s21, 0x30000
	s_mov_b32 s24, 0x60000
	s_mov_b32 s25, 0x90000
	v_lshlrev_b32_e32 v168, 1, v4
	s_mov_b64 s[10:11], 0x1000
	s_movk_i32 s27, 0x1000
	v_add_u32_e32 v227, v218, v7
	v_add_u32_e32 v228, v218, v9
	v_lshlrev_b32_e32 v150, 1, v150
	s_mov_b32 s36, 0xc0000
	s_mov_b32 s37, 0xf0000
	s_mov_b32 s38, 0x120000
	s_mov_b32 s39, 0x150000
	s_mov_b32 s40, 0xc1000
	v_add_u32_e32 v229, v14, v13
	v_add_u32_e32 v230, s12, v15
	v_add_u32_e32 v231, v8, v217
	s_mov_b64 s[12:13], 0x4000
	v_mov_b32_e32 v232, 0x42800000
	v_not_b32_e32 v233, 63
	v_mov_b32_e32 v165, v151
	v_mov_b32_e32 v167, v151
	v_mov_b32_e32 v169, v151
	v_add_u32_e32 v234, v11, v12
	s_mov_b32 s41, s100
	s_branch .LBB0_362

	.amdhsa_kernel _Z4mega6Params
		.amdhsa_group_segment_fixed_size 0
		.amdhsa_private_segment_fixed_size 0
		.amdhsa_kernarg_size 440
		.amdhsa_user_sgpr_count 2
		.amdhsa_user_sgpr_dispatch_ptr 0
		.amdhsa_user_sgpr_queue_ptr 0
		.amdhsa_user_sgpr_kernarg_segment_ptr 1
		.amdhsa_user_sgpr_dispatch_id 0
		.amdhsa_user_sgpr_kernarg_preload_length 0
		.amdhsa_user_sgpr_kernarg_preload_offset 0
		.amdhsa_user_sgpr_private_segment_size 0
		.amdhsa_uses_dynamic_stack 0
		.amdhsa_enable_private_segment 0
		.amdhsa_system_sgpr_workgroup_id_x 1
		.amdhsa_system_sgpr_workgroup_id_y 0
		.amdhsa_system_sgpr_workgroup_id_z 0
		.amdhsa_system_sgpr_workgroup_info 0
		.amdhsa_system_vgpr_workitem_id 2
		.amdhsa_next_free_vgpr 256
		.amdhsa_next_free_sgpr 102
		.amdhsa_accum_offset 256
		.amdhsa_reserve_vcc 1
		.amdhsa_float_round_mode_32 0
		.amdhsa_float_round_mode_16_64 0
		.amdhsa_float_denorm_mode_32 3
		.amdhsa_float_denorm_mode_16_64 3
		.amdhsa_dx10_clamp 1
		.amdhsa_ieee_mode 1
		.amdhsa_fp16_overflow 0
		.amdhsa_tg_split 0
		.amdhsa_exception_fp_ieee_invalid_op 0
		.amdhsa_exception_fp_denorm_src 0
		.amdhsa_exception_fp_ieee_div_zero 0
		.amdhsa_exception_fp_ieee_overflow 0
		.amdhsa_exception_fp_ieee_underflow 0
		.amdhsa_exception_fp_ieee_inexact 0
		.amdhsa_exception_int_div_zero 0
	.end_amdhsa_kernel

amdhsa.kernels:
  - .agpr_count:     0
    .args:
      - .offset:         0
        .size:           184
        .value_kind:     by_value
      - .offset:         184
        .size:           4
        .value_kind:     hidden_block_count_x
      - .offset:         188
        .size:           4
        .value_kind:     hidden_block_count_y
      - .offset:         192
        .size:           4
        .value_kind:     hidden_block_count_z
      - .offset:         196
        .size:           2
        .value_kind:     hidden_group_size_x
      - .offset:         198
        .size:           2
        .value_kind:     hidden_group_size_y
      - .offset:         200
        .size:           2
        .value_kind:     hidden_group_size_z
      - .offset:         202
        .size:           2
        .value_kind:     hidden_remainder_x
      - .offset:         204
        .size:           2
        .value_kind:     hidden_remainder_y
      - .offset:         206
        .size:           2
        .value_kind:     hidden_remainder_z
      - .offset:         224
        .size:           8
        .value_kind:     hidden_global_offset_x
      - .offset:         232
        .size:           8
        .value_kind:     hidden_global_offset_y
      - .offset:         240
        .size:           8
        .value_kind:     hidden_global_offset_z
      - .offset:         248
        .size:           2
        .value_kind:     hidden_grid_dims
      - .offset:         272
        .size:           8
        .value_kind:     hidden_multigrid_sync_arg
      - .offset:         304
        .size:           4
        .value_kind:     hidden_dynamic_lds_size
    .group_segment_fixed_size: 0
    .kernarg_segment_align: 8
    .kernarg_segment_size: 440
    .language:       OpenCL C
    .language_version:
      - 2
      - 0
    .max_flat_workgroup_size: 512
    .name:           _Z4mega6Params
    .private_segment_fixed_size: 0
    .sgpr_count:     108
    .sgpr_spill_count: 41
    .symbol:         _Z4mega6Params.kd
    .uniform_work_group_size: 1
    .uses_dynamic_stack: false
    .vgpr_count:     256
    .vgpr_spill_count: 0
    .wavefront_size: 64
